# RS8 row-scale loads in GU and IN epilogues de-serialized: 8 rows in one round trip, cross-lane reduce
# speedup vs baseline: 1.0108x; 1.0108x over previous
; __device__ __forceinline__ float row_rs(const float* ssq, unsigned row) {
;     const f32x4* sp = (const f32x4*)(ssq + (size_t)row * 16); const f32x4 a = (sp[0] + sp[1]) + (sp[2] + sp[3]);
;     return __builtin_amdgcn_rsqf(((a[0] + a[1]) + (a[2] + a[3])) * (1.0f / 1024.0f) + RMS_EPS);
; }
.LBB0_576:
	v_lshl_add_u32 v192, s71, 8, v9
	s_mov_b64 s[8:9], -1
	s_cmp_eq_u32 s71, s1
	v_or_b32_e32 v190, 16, v192
	v_or_b32_e32 v188, 32, v192
	v_or_b32_e32 v186, 48, v192
	v_add_u32_e32 v184, 0x80, v192
	v_add_u32_e32 v182, 0x90, v192
	v_add_u32_e32 v180, 0xa0, v192
	v_add_u32_e32 v178, 0xb0, v192
	s_cbranch_scc1 .LBB0_579
	v_mov_b32_e32 v193, v8
	v_mov_b32_e32 v191, v8
	v_mov_b32_e32 v189, v8
	v_mov_b32_e32 v187, v8
	v_mov_b32_e32 v185, v8
	v_mov_b32_e32 v183, v8
	v_mov_b32_e32 v181, v8
	v_mov_b32_e32 v179, v8
	v_lshrrev_b32_e32 v197, 4, v202
	v_lshlrev_b32_e32 v196, 6, v192
	v_lshl_add_u32 v196, v197, 4, v196
	v_add_u32_e32 v197, 0x2000, v196
	global_load_dwordx4 v[210:213], v196, s[12:13]
	global_load_dwordx4 v[214:217], v196, s[12:13] offset:1024
	global_load_dwordx4 v[218:221], v196, s[12:13] offset:2048
	global_load_dwordx4 v[222:225], v196, s[12:13] offset:3072
	global_load_dwordx4 v[226:229], v197, s[12:13]
	global_load_dwordx4 v[230:233], v197, s[12:13] offset:1024
	global_load_dwordx4 v[234:237], v197, s[12:13] offset:2048
	global_load_dwordx4 v[238:241], v197, s[12:13] offset:3072
	v_xor_b32_e32 v242, 16, v202
	v_xor_b32_e32 v243, 32, v202
	v_lshlrev_b32_e32 v242, 2, v242
	v_lshlrev_b32_e32 v243, 2, v243
	s_waitcnt vmcnt(0)
	v_pk_add_f32 v[210:211], v[210:211], v[212:213]
	v_pk_add_f32 v[214:215], v[214:215], v[216:217]
	v_pk_add_f32 v[218:219], v[218:219], v[220:221]
	v_pk_add_f32 v[222:223], v[222:223], v[224:225]
	v_pk_add_f32 v[226:227], v[226:227], v[228:229]
	v_pk_add_f32 v[230:231], v[230:231], v[232:233]
	v_pk_add_f32 v[234:235], v[234:235], v[236:237]
	v_pk_add_f32 v[238:239], v[238:239], v[240:241]
	v_add_f32_e32 v210, v210, v211
	v_add_f32_e32 v214, v214, v215
	v_add_f32_e32 v218, v218, v219
	v_add_f32_e32 v222, v222, v223
	v_add_f32_e32 v226, v226, v227
	v_add_f32_e32 v230, v230, v231
	v_add_f32_e32 v234, v234, v235
	v_add_f32_e32 v238, v238, v239
	ds_bpermute_b32 v138, v242, v210
	ds_bpermute_b32 v139, v242, v214
	ds_bpermute_b32 v140, v242, v218
	ds_bpermute_b32 v141, v242, v222
	ds_bpermute_b32 v142, v242, v226
	ds_bpermute_b32 v143, v242, v230
	ds_bpermute_b32 v144, v242, v234
	ds_bpermute_b32 v145, v242, v238
	s_waitcnt lgkmcnt(0)
	v_add_f32_e32 v210, v210, v138
	v_add_f32_e32 v214, v214, v139
	v_add_f32_e32 v218, v218, v140
	v_add_f32_e32 v222, v222, v141
	v_add_f32_e32 v226, v226, v142
	v_add_f32_e32 v230, v230, v143
	v_add_f32_e32 v234, v234, v144
	v_add_f32_e32 v238, v238, v145
	ds_bpermute_b32 v138, v243, v210
	ds_bpermute_b32 v139, v243, v214
	ds_bpermute_b32 v140, v243, v218
	ds_bpermute_b32 v141, v243, v222
	ds_bpermute_b32 v142, v243, v226
	ds_bpermute_b32 v143, v243, v230
	ds_bpermute_b32 v144, v243, v234
	ds_bpermute_b32 v145, v243, v238
	s_waitcnt lgkmcnt(0)
	v_add_f32_e32 v210, v210, v138
	v_add_f32_e32 v214, v214, v139
	v_add_f32_e32 v218, v218, v140
	v_add_f32_e32 v222, v222, v141
	v_add_f32_e32 v226, v226, v142
	v_add_f32_e32 v230, v230, v143
	v_add_f32_e32 v234, v234, v144
	v_add_f32_e32 v238, v238, v145
	v_fmamk_f32 v0, v210, 0x3a800000, v203
	v_fmamk_f32 v1, v214, 0x3a800000, v203
	v_fmamk_f32 v2, v218, 0x3a800000, v203
	v_fmamk_f32 v3, v222, 0x3a800000, v203
	v_fmamk_f32 v4, v226, 0x3a800000, v203
	v_fmamk_f32 v5, v230, 0x3a800000, v203
	v_fmamk_f32 v6, v234, 0x3a800000, v203
	v_fmamk_f32 v7, v238, 0x3a800000, v203
	v_rsq_f32_e32 v0, v0
	v_rsq_f32_e32 v1, v1
	v_rsq_f32_e32 v2, v2
	v_rsq_f32_e32 v3, v3
	v_rsq_f32_e32 v4, v4
	v_rsq_f32_e32 v5, v5
	v_rsq_f32_e32 v6, v6
	v_rsq_f32_e32 v7, v7
	v_add_u32_e32 v138, 0, v159
	v_add_u32_e32 v138, 0x20100, v138
	ds_write_b128 v138, v[0:3]
	ds_write_b128 v138, v[4:7] offset:16
	s_cbranch_execz .LBB0_580

; __device__ __forceinline__ float row_rs(const float* ssq, unsigned row) {
;     const f32x4* sp = (const f32x4*)(ssq + (size_t)row * 16); const f32x4 a = (sp[0] + sp[1]) + (sp[2] + sp[3]);
;     return __builtin_amdgcn_rsqf(((a[0] + a[1]) + (a[2] + a[3])) * (1.0f / 1024.0f) + RMS_EPS);
; }
.LBB0_701:
	v_lshl_add_u32 v186, s68, 8, v9
	v_add_u32_e32 v0, 0, v159
	s_mov_b64 s[22:23], -1
	s_cmp_eq_u32 s68, s70
	v_or_b32_e32 v190, 16, v186
	v_or_b32_e32 v191, 32, v186
	v_or_b32_e32 v193, 48, v186
	v_add_u32_e32 v192, 0x80, v186
	v_add_u32_e32 v194, 0x20100, v0
	s_cbranch_scc1 .LBB0_703
	v_mov_b32_e32 v187, v8
	v_or_b32_e32 v184, 16, v186
	v_mov_b32_e32 v185, v8
	v_or_b32_e32 v182, 32, v186
	v_mov_b32_e32 v183, v8
	v_or_b32_e32 v180, 48, v186
	v_mov_b32_e32 v181, v8
	v_add_u32_e32 v178, 0x80, v186
	v_mov_b32_e32 v179, v8
	s_mov_b64 s[22:23], 0
	v_lshrrev_b32_e32 v196, 4, v202
	v_lshlrev_b32_e32 v195, 6, v186
	v_lshl_add_u32 v195, v196, 4, v195
	v_add_u32_e32 v196, 0x2000, v195
	global_load_dwordx4 v[210:213], v195, s[10:11]
	global_load_dwordx4 v[214:217], v195, s[10:11] offset:1024
	global_load_dwordx4 v[218:221], v195, s[10:11] offset:2048
	global_load_dwordx4 v[222:225], v195, s[10:11] offset:3072
	global_load_dwordx4 v[226:229], v196, s[10:11]
	global_load_dwordx4 v[230:233], v196, s[10:11] offset:1024
	global_load_dwordx4 v[234:237], v196, s[10:11] offset:2048
	global_load_dwordx4 v[238:241], v196, s[10:11] offset:3072
	v_xor_b32_e32 v242, 16, v202
	v_xor_b32_e32 v243, 32, v202
	v_lshlrev_b32_e32 v242, 2, v242
	v_lshlrev_b32_e32 v243, 2, v243
	s_waitcnt vmcnt(0)
	v_pk_add_f32 v[210:211], v[210:211], v[212:213]
	v_pk_add_f32 v[214:215], v[214:215], v[216:217]
	v_pk_add_f32 v[218:219], v[218:219], v[220:221]
	v_pk_add_f32 v[222:223], v[222:223], v[224:225]
	v_pk_add_f32 v[226:227], v[226:227], v[228:229]
	v_pk_add_f32 v[230:231], v[230:231], v[232:233]
	v_pk_add_f32 v[234:235], v[234:235], v[236:237]
	v_pk_add_f32 v[238:239], v[238:239], v[240:241]
	v_add_f32_e32 v210, v210, v211
	v_add_f32_e32 v214, v214, v215
	v_add_f32_e32 v218, v218, v219
	v_add_f32_e32 v222, v222, v223
	v_add_f32_e32 v226, v226, v227
	v_add_f32_e32 v230, v230, v231
	v_add_f32_e32 v234, v234, v235
	v_add_f32_e32 v238, v238, v239
	ds_bpermute_b32 v138, v242, v210
	ds_bpermute_b32 v139, v242, v214
	ds_bpermute_b32 v140, v242, v218
	ds_bpermute_b32 v141, v242, v222
	ds_bpermute_b32 v142, v242, v226
	ds_bpermute_b32 v143, v242, v230
	ds_bpermute_b32 v144, v242, v234
	ds_bpermute_b32 v145, v242, v238
	s_waitcnt lgkmcnt(0)
	v_add_f32_e32 v210, v210, v138
	v_add_f32_e32 v214, v214, v139
	v_add_f32_e32 v218, v218, v140
	v_add_f32_e32 v222, v222, v141
	v_add_f32_e32 v226, v226, v142
	v_add_f32_e32 v230, v230, v143
	v_add_f32_e32 v234, v234, v144
	v_add_f32_e32 v238, v238, v145
	ds_bpermute_b32 v138, v243, v210
	ds_bpermute_b32 v139, v243, v214
	ds_bpermute_b32 v140, v243, v218
	ds_bpermute_b32 v141, v243, v222
	ds_bpermute_b32 v142, v243, v226
	ds_bpermute_b32 v143, v243, v230
	ds_bpermute_b32 v144, v243, v234
	ds_bpermute_b32 v145, v243, v238
	s_waitcnt lgkmcnt(0)
	v_add_f32_e32 v210, v210, v138
	v_add_f32_e32 v214, v214, v139
	v_add_f32_e32 v218, v218, v140
	v_add_f32_e32 v222, v222, v141
	v_add_f32_e32 v226, v226, v142
	v_add_f32_e32 v230, v230, v143
	v_add_f32_e32 v234, v234, v144
	v_add_f32_e32 v238, v238, v145
	v_fmamk_f32 v0, v210, 0x3a800000, v203
	v_fmamk_f32 v1, v214, 0x3a800000, v203
	v_fmamk_f32 v2, v218, 0x3a800000, v203
	v_fmamk_f32 v3, v222, 0x3a800000, v203
	v_fmamk_f32 v4, v226, 0x3a800000, v203
	v_fmamk_f32 v5, v230, 0x3a800000, v203
	v_fmamk_f32 v6, v234, 0x3a800000, v203
	v_fmamk_f32 v7, v238, 0x3a800000, v203
	v_rsq_f32_e32 v0, v0
	v_rsq_f32_e32 v1, v1
	v_rsq_f32_e32 v2, v2
	v_rsq_f32_e32 v3, v3
	v_rsq_f32_e32 v4, v4
	v_rsq_f32_e32 v5, v5
	v_rsq_f32_e32 v6, v6
	v_rsq_f32_e32 v7, v7
	s_nop 0
	ds_write_b128 v194, v[0:3]
	ds_write_b128 v194, v[4:7] offset:16
